# S5 scan: u rows prefetched one block ahead, y store left in flight, both recurrences as plain FMAs with (B u) rows read four tokens ahead
# speedup vs baseline: 1.0163x; 1.0067x over previous
; #define MFMA16(a, b, c) __builtin_amdgcn_mfma_f32_16x16x32_bf16(a, b, c, 0, 0, 0)
; __device__ __forceinline__ void s5_phase(LAS unsigned char* lds, const bf16_t* USSM, const float* S5A, const float* S5B, const float* c_re, const float* c_im, const float* dskip,
;                                          bf16_t* YSSM, int tid, int lane, int wave) {
;     ...
;         const float are = S5A[(g * 64 + lane) * 2], aim = S5A[(g * 64 + lane) * 2 + 1];
;         bf16x8 bfr[8], cfr[4];
; #pragma unroll
;         for (int nt = 0; nt < 8; ++nt) { const int pp = nt * 16 + r16, p = pp & 63, im = pp >> 6; bfr[nt] = q4 < 2 ? pack_bf8(S5B + (size_t)(g * 64 + p) * 32 + im * 16 + q4 * 8, 1.f) : zf; }
; #pragma unroll
;         for (int ks = 0; ks < 4; ++ks) { const int pp = ks * 32 + q4 * 8, p = pp & 63, im = pp >> 6; cfr[ks] = pack_bf8((im ? c_im : c_re) + (size_t)(g * 16 + r16) * 64 + p, im ? -1.f : 1.f); }
;         const float dsk = dskip[g * 16 + r16];
;         const bf16_t* ub = USSM + ((size_t)(b * SEQ + wave * 1024)) * 1024 + g * 16;
;         float xr = 0.f, xi = 0.f;
;         for (int tb = 0; tb < 64; ++tb) {
;             bf16x8 a = *(const bf16x8*)(ub + (size_t)(tb * 16 + r16) * 1024 + (q4 & 1) * 8); if (q4 >= 2) a = zf;
; #pragma unroll
;             for (int nt = 0; nt < 8; ++nt) { const f32x4 acc = MFMA16(a, bfr[nt], z4);
; #pragma unroll
;                 for (int i = 0; i < 4; ++i) BU[(q4 * 4 + i) * 132 + nt * 16 + r16] = acc[i]; }
.LBB0_584:
	s_or_b64 exec, exec, s[14:15]
	v_lshl_or_b32 v82, s6, 12, v117
	v_lshl_add_u64 v[40:41], v[88:89], 0, v[82:83]
	global_load_dwordx4 v[32:35], v[40:41], off
	global_load_dwordx4 v[36:39], v[40:41], off offset:16
	v_lshl_add_u64 v[50:51], v[90:91], 0, v[82:83]
	s_lshl_b32 s6, s6, 4
	v_or_b32_e32 v49, s6, v81
	v_lshlrev_b32_e32 v49, 2, v49
	s_and_b32 s14, s27, 0xffffe000
	s_add_i32 s46, s3, s14
	s_ashr_i32 s47, s46, 31
	s_and_b32 s12, s42, 63
	s_lshl_b64 s[46:47], s[46:47], 11
	s_lshl_b32 s12, s12, 5
	s_or_b32 s46, s46, s12
	v_lshl_add_u64 v[96:97], v[92:93], 0, s[46:47]
	s_waitcnt vmcnt(2)
	v_pk_mov_b32 v[98:99], v[94:95], v[94:95] op_sel:[1,0]
	s_mov_b64 s[58:59], 0
	s_waitcnt vmcnt(1)
	v_cvt_pk_bf16_f32 v32, v32, v33
	v_cvt_pk_bf16_f32 v33, v34, v35
	s_waitcnt vmcnt(0)
	v_cvt_pk_bf16_f32 v34, v36, v37
	v_cvt_pk_bf16_f32 v35, v38, v39
	global_load_dwordx4 v[36:39], v[40:41], off offset:128
	s_nop 0
	global_load_dwordx4 v[40:43], v[40:41], off offset:144
	s_waitcnt vmcnt(1)
	v_cvt_pk_bf16_f32 v36, v36, v37
	v_cvt_pk_bf16_f32 v37, v38, v39
	s_waitcnt vmcnt(0)
	v_cvt_pk_bf16_f32 v38, v40, v41
	v_cvt_pk_bf16_f32 v39, v42, v43
	global_load_dwordx4 v[40:43], v[50:51], off
	global_load_dwordx4 v[44:47], v[50:51], off offset:16
	s_waitcnt vmcnt(1)
	v_xor_b32_e32 v40, 0x80000000, v40
	v_xor_b32_e32 v41, 0x80000000, v41
	v_xor_b32_e32 v42, 0x80000000, v42
	v_xor_b32_e32 v43, 0x80000000, v43
	s_waitcnt vmcnt(0)
	v_xor_b32_e32 v44, 0x80000000, v44
	v_xor_b32_e32 v45, 0x80000000, v45
	v_xor_b32_e32 v46, 0x80000000, v46
	v_xor_b32_e32 v47, 0x80000000, v47
	v_cvt_pk_bf16_f32 v40, v40, v41
	v_cvt_pk_bf16_f32 v41, v42, v43
	v_cvt_pk_bf16_f32 v42, v44, v45
	v_cvt_pk_bf16_f32 v43, v46, v47
	global_load_dwordx4 v[44:47], v[50:51], off offset:128
	s_nop 0
	global_load_dwordx4 v[50:53], v[50:51], off offset:144
	s_waitcnt vmcnt(1)
	v_xor_b32_e32 v44, 0x80000000, v44
	v_xor_b32_e32 v45, 0x80000000, v45
	v_xor_b32_e32 v46, 0x80000000, v46
	v_xor_b32_e32 v47, 0x80000000, v47
	s_waitcnt vmcnt(0)
	v_xor_b32_e32 v50, 0x80000000, v50
	v_xor_b32_e32 v51, 0x80000000, v51
	v_xor_b32_e32 v52, 0x80000000, v52
	v_xor_b32_e32 v53, 0x80000000, v53
	v_cvt_pk_bf16_f32 v44, v44, v45
	v_cvt_pk_bf16_f32 v45, v46, v47
	v_cvt_pk_bf16_f32 v46, v50, v51
	v_cvt_pk_bf16_f32 v47, v52, v53
	global_load_dword v123, v49, s[82:83]
	v_mov_b32_e32 v49, v48
	v_lshl_add_u64 v[156:157], v[96:97], 0, s[58:59]
	global_load_dwordx4 v[148:151], v[156:157], off
.LBB0_585:
	v_add_u32_e32 v124, 0x1000, v122
	v_mov_b32_e32 v158, v48
	v_mov_b32_e32 v159, v49
	v_add_u32_e32 v125, 0x1400, v122
	v_add_u32_e32 v126, 16, v111
	v_add_u32_e32 v127, 32, v111
	v_add_u32_e32 v128, 48, v111
	v_add_u32_e32 v129, 64, v111
	v_add_u32_e32 v130, 0x50, v111
	v_add_u32_e32 v131, 0x60, v111
	v_add_u32_e32 v132, 0x70, v111
	v_add_u32_e32 v133, 0x80, v111
	v_add_u32_e32 v134, 0x90, v111
	v_add_u32_e32 v135, 0xa0, v111
	v_add_u32_e32 v136, 0xb0, v111
	v_add_u32_e32 v137, 0xc0, v111
	v_add_u32_e32 v138, 0xd0, v111
	v_add_u32_e32 v139, 0xe0, v111
	v_add_u32_e32 v140, 0xf0, v111
	s_add_u32 s58, s58, 0x8000
	s_addc_u32 s59, s59, 0
	s_cmp_eq_u32 s58, 0x200000
	s_waitcnt vmcnt(0)
	v_cndmask_b32_e64 v53, v151, 0, s[4:5]
	v_cndmask_b32_e64 v52, v150, 0, s[4:5]
	v_cndmask_b32_e64 v51, v149, 0, s[4:5]
	v_cndmask_b32_e64 v50, v148, 0, s[4:5]
	v_lshl_add_u64 v[156:157], v[96:97], 0, s[58:59]
	global_load_dwordx4 v[148:151], v[156:157], off
	s_nop 1
	v_mfma_f32_16x16x32_bf16 v[54:57], v[50:53], v[0:3], 0
	v_mfma_f32_16x16x32_bf16 v[58:61], v[50:53], v[4:7], 0
	v_mfma_f32_16x16x32_bf16 v[62:65], v[50:53], v[8:11], 0
	v_mfma_f32_16x16x32_bf16 v[66:69], v[50:53], v[16:19], 0
	v_mfma_f32_16x16x32_bf16 v[70:73], v[50:53], v[12:15], 0
	v_mfma_f32_16x16x32_bf16 v[74:77], v[50:53], v[20:23], 0
	v_mfma_f32_16x16x32_bf16 v[100:103], v[50:53], v[24:27], 0
	v_mfma_f32_16x16x32_bf16 v[48:51], v[50:53], v[28:31], 0
	s_nop 1
	ds_write2_b32 v124, v54, v58 offset1:16
	ds_write2_b32 v124, v55, v59 offset0:132 offset1:148
	ds_write2_b32 v125, v56, v60 offset0:8 offset1:24
	ds_write2_b32 v125, v57, v61 offset0:140 offset1:156
	ds_write2_b32 v124, v62, v66 offset0:32 offset1:48
	ds_write2_b32 v124, v63, v67 offset0:164 offset1:180
	ds_write2_b32 v125, v64, v68 offset0:40 offset1:56
	ds_write2_b32 v125, v65, v69 offset0:172 offset1:188
	ds_write2_b32 v124, v70, v74 offset0:64 offset1:80
	ds_write2_b32 v124, v71, v75 offset0:196 offset1:212
	ds_write2_b32 v125, v72, v76 offset0:72 offset1:88
	ds_write2_b32 v125, v73, v77 offset0:204 offset1:220
	ds_write2_b32 v124, v100, v48 offset0:96 offset1:112
	ds_write2_b32 v124, v101, v49 offset0:228 offset1:244
	ds_write2_b32 v125, v102, v50 offset0:104 offset1:120
	ds_write2_b32 v125, v103, v51 offset0:236 offset1:252
	s_waitcnt lgkmcnt(0)
; #define LDS_WAIT() asm volatile("s_waitcnt lgkmcnt(0)" ::: "memory")
; __device__ __forceinline__ void s5_phase(LAS unsigned char* lds, const bf16_t* USSM, const float* S5A, const float* S5B, const float* c_re, const float* c_im, const float* dskip,
;                                          bf16_t* YSSM, int tid, int lane, int wave) {
;     ...
;             LDS_WAIT();
; #pragma unroll
;             for (int t = 0; t < 16; ++t) { const float br = BU[t * 132 + lane], bi = BU[t * 132 + 64 + lane];
;                 const float nr = are * xr - aim * xi + br, ni = are * xi + aim * xr + bi; xr = nr; xi = ni; }
;             LDS_WAIT();
;         }
;         carry[(wave * 64 + lane) * 2] = xr; carry[(wave * 64 + lane) * 2 + 1] = xi;
;         __syncthreads();
;         float pr = are, pi = aim;
; #pragma unroll
;         for (int k = 0; k < 10; ++k) { const float t2 = pr * pr - pi * pi; pi = 2.f * pr * pi; pr = t2; }
;         xr = 0.f; xi = 0.f;
;         for (int k = 0; k < wave; ++k) { const float er = carry[(k * 64 + lane) * 2], ei = carry[(k * 64 + lane) * 2 + 1]; const float nr = pr * xr - pi * xi + er, ni = pr * xi + pi * xr + ei; xr = nr; xi = ni; }
	ds_read2st64_b32 v[48:49], v111 offset0:16 offset1:17
	ds_read2st64_b32 v[50:51], v126 offset0:18 offset1:19
	ds_read2st64_b32 v[52:53], v127 offset0:20 offset1:21
	ds_read2st64_b32 v[54:55], v128 offset0:22 offset1:23
	ds_read2st64_b32 v[56:57], v129 offset0:24 offset1:25
	ds_read2st64_b32 v[58:59], v130 offset0:26 offset1:27
	ds_read2st64_b32 v[60:61], v131 offset0:28 offset1:29
	ds_read2st64_b32 v[62:63], v132 offset0:30 offset1:31
	ds_read2st64_b32 v[64:65], v133 offset0:32 offset1:33
	ds_read2st64_b32 v[66:67], v134 offset0:34 offset1:35
	ds_read2st64_b32 v[68:69], v135 offset0:36 offset1:37
	ds_read2st64_b32 v[70:71], v136 offset0:38 offset1:39
	ds_read2st64_b32 v[72:73], v137 offset0:40 offset1:41
	ds_read2st64_b32 v[74:75], v138 offset0:42 offset1:43
	ds_read2st64_b32 v[76:77], v139 offset0:44 offset1:45
	ds_read2st64_b32 v[78:79], v140 offset0:46 offset1:47
	s_waitcnt lgkmcnt(15)
	v_fma_f32 v160, v94, v158, v48
	v_fma_f32 v161, v94, v159, v49
	v_fma_f32 v162, -v95, v159, v160
	v_fma_f32 v163, v95, v158, v161
	s_waitcnt lgkmcnt(14)
	v_fma_f32 v160, v94, v162, v50
	v_fma_f32 v161, v94, v163, v51
	v_fma_f32 v158, -v95, v163, v160
	v_fma_f32 v159, v95, v162, v161
	s_waitcnt lgkmcnt(13)
	v_fma_f32 v160, v94, v158, v52
	v_fma_f32 v161, v94, v159, v53
	v_fma_f32 v162, -v95, v159, v160
	v_fma_f32 v163, v95, v158, v161
	s_waitcnt lgkmcnt(12)
	v_fma_f32 v160, v94, v162, v54
	v_fma_f32 v161, v94, v163, v55
	v_fma_f32 v158, -v95, v163, v160
	v_fma_f32 v159, v95, v162, v161
	s_waitcnt lgkmcnt(11)
	v_fma_f32 v160, v94, v158, v56
	v_fma_f32 v161, v94, v159, v57
	v_fma_f32 v162, -v95, v159, v160
	v_fma_f32 v163, v95, v158, v161
	s_waitcnt lgkmcnt(10)
	v_fma_f32 v160, v94, v162, v58
	v_fma_f32 v161, v94, v163, v59
	v_fma_f32 v158, -v95, v163, v160
	v_fma_f32 v159, v95, v162, v161
	s_waitcnt lgkmcnt(9)
	v_fma_f32 v160, v94, v158, v60
	v_fma_f32 v161, v94, v159, v61
	v_fma_f32 v162, -v95, v159, v160
	v_fma_f32 v163, v95, v158, v161
	s_waitcnt lgkmcnt(8)
	v_fma_f32 v160, v94, v162, v62
	v_fma_f32 v161, v94, v163, v63
	v_fma_f32 v158, -v95, v163, v160
	v_fma_f32 v159, v95, v162, v161
	s_waitcnt lgkmcnt(7)
	v_fma_f32 v160, v94, v158, v64
	v_fma_f32 v161, v94, v159, v65
	v_fma_f32 v162, -v95, v159, v160
	v_fma_f32 v163, v95, v158, v161
	s_waitcnt lgkmcnt(6)
	v_fma_f32 v160, v94, v162, v66
	v_fma_f32 v161, v94, v163, v67
	v_fma_f32 v158, -v95, v163, v160
	v_fma_f32 v159, v95, v162, v161
	s_waitcnt lgkmcnt(5)
	v_fma_f32 v160, v94, v158, v68
	v_fma_f32 v161, v94, v159, v69
	v_fma_f32 v162, -v95, v159, v160
	v_fma_f32 v163, v95, v158, v161
	s_waitcnt lgkmcnt(4)
	v_fma_f32 v160, v94, v162, v70
	v_fma_f32 v161, v94, v163, v71
	v_fma_f32 v158, -v95, v163, v160
	v_fma_f32 v159, v95, v162, v161
	s_waitcnt lgkmcnt(3)
	v_fma_f32 v160, v94, v158, v72
	v_fma_f32 v161, v94, v159, v73
	v_fma_f32 v162, -v95, v159, v160
	v_fma_f32 v163, v95, v158, v161
	s_waitcnt lgkmcnt(2)
	v_fma_f32 v160, v94, v162, v74
	v_fma_f32 v161, v94, v163, v75
	v_fma_f32 v158, -v95, v163, v160
	v_fma_f32 v159, v95, v162, v161
	s_waitcnt lgkmcnt(1)
	v_fma_f32 v160, v94, v158, v76
	v_fma_f32 v161, v94, v159, v77
	v_fma_f32 v162, -v95, v159, v160
	v_fma_f32 v163, v95, v158, v161
	s_waitcnt lgkmcnt(0)
	v_fma_f32 v160, v94, v162, v78
	v_fma_f32 v161, v94, v163, v79
	v_fma_f32 v48, -v95, v163, v160
	v_fma_f32 v49, v95, v162, v161
	s_cbranch_scc0 .LBB0_585
	s_andn2_b64 vcc, exec, s[8:9]
	ds_write_b64 v107, v[48:49]
	s_waitcnt lgkmcnt(0)
	s_barrier
	s_cbranch_vccnz .LBB0_591
	v_pk_mul_f32 v[48:49], v[94:95], v[94:95]
	s_andn2_b64 vcc, exec, s[18:19]
	v_sub_f32_e32 v48, v48, v49
	v_add_f32_e32 v49, v94, v94
	v_mul_f32_e32 v49, v95, v49
	v_mul_f32_e32 v50, v48, v48
	v_add_f32_e32 v48, v48, v48
	v_mul_f32_e32 v48, v49, v48
	v_fma_f32 v50, -v49, v49, v50
	v_mul_f32_e32 v49, v48, v48
	v_fma_f32 v49, v50, v50, -v49
	v_add_f32_e32 v50, v50, v50
	v_mul_f32_e32 v48, v48, v50
	v_mul_f32_e32 v50, v48, v48
	v_fma_f32 v50, v49, v49, -v50
	v_add_f32_e32 v49, v49, v49
	v_mul_f32_e32 v48, v48, v49
	v_mul_f32_e32 v49, v48, v48
	v_fma_f32 v49, v50, v50, -v49
	v_add_f32_e32 v50, v50, v50
	v_mul_f32_e32 v48, v48, v50
	v_mul_f32_e32 v50, v48, v48
	v_fma_f32 v50, v49, v49, -v50
	v_add_f32_e32 v49, v49, v49
	v_mul_f32_e32 v48, v48, v49
	v_mul_f32_e32 v49, v48, v48
	v_fma_f32 v49, v50, v50, -v49
	v_add_f32_e32 v50, v50, v50
	v_mul_f32_e32 v48, v48, v50
	v_mul_f32_e32 v50, v48, v48
	v_fma_f32 v50, v49, v49, -v50
	v_add_f32_e32 v49, v49, v49
	v_mul_f32_e32 v48, v48, v49
	v_mul_f32_e32 v49, v48, v48
	v_fma_f32 v49, v50, v50, -v49
	v_add_f32_e32 v50, v50, v50
	v_mul_f32_e32 v50, v48, v50
	v_mul_f32_e32 v48, v50, v50
	v_fma_f32 v48, v49, v49, -v48
	v_add_f32_e32 v49, v49, v49
	v_mul_f32_e32 v50, v50, v49
	s_cbranch_vccnz .LBB0_592
	v_mov_b32_e32 v76, 0
	v_mov_b32_e32 v49, v48
	v_mov_b32_e32 v51, v50
	s_mov_b32 s15, 0
	v_mov_b32_e32 v52, v108
	v_mov_b32_e32 v77, v76

; #define LAS __attribute__((address_space(3)))
; #define LDS_WAIT() asm volatile("s_waitcnt lgkmcnt(0)" ::: "memory")
; #define MFMA16(a, b, c) __builtin_amdgcn_mfma_f32_16x16x32_bf16(a, b, c, 0, 0, 0)
; __device__ __forceinline__ bf16_t tobf(float x) { return (bf16_t)pk2(x, 0.f); }
; __device__ __forceinline__ void s5_phase(LAS unsigned char* lds, const bf16_t* USSM, const float* S5A, const float* S5B, const float* c_re, const float* c_im, const float* dskip,
;                                          bf16_t* YSSM, int tid, int lane, int wave) {
;     ...
;         for (int tb = 0; tb < 64; ++tb) {
;             bf16x8 a = *(const bf16x8*)(ub + (size_t)(tb * 16 + r16) * 1024 + (q4 & 1) * 8); *(LAS bf16x8*)(UST + r16 * 16 + (q4 & 1) * 8) = a; if (q4 >= 2) a = zf;
; #pragma unroll
;             for (int nt = 0; nt < 8; ++nt) { const f32x4 acc = MFMA16(a, bfr[nt], z4);
; #pragma unroll
;                 for (int i = 0; i < 4; ++i) BU[(q4 * 4 + i) * 132 + nt * 16 + r16] = acc[i]; }
;             LDS_WAIT();
; #pragma unroll
;             for (int t = 0; t < 16; ++t) { const float br = BU[t * 132 + lane], bi = BU[t * 132 + 64 + lane];
;                 const float nr = are * xr - aim * xi + br, ni = are * xi + aim * xr + bi; xr = nr; xi = ni;
;                 XB[t * 136 + lane] = tobf(xr); XB[t * 136 + 64 + lane] = tobf(xi); }
.LBB0_595:
	s_lshl_b32 s6, s6, 1
	v_add_u32_e32 v82, s14, v116
	v_lshl_add_u64 v[100:101], v[84:85], 0, s[6:7]
	s_mov_b32 s6, 0
	global_load_dwordx4 v[148:151], v[96:97], off
	v_lshl_add_u64 v[96:97], v[96:97], 0, s[56:57]
	s_waitcnt vmcnt(0)
.LBB0_596:
	v_mov_b32_e32 v158, v76
	v_mov_b32_e32 v159, v77
	v_add_u32_e32 v141, v115, v112
	v_add_u32_e32 v146, s6, v82
	v_add_u32_e32 v104, 0x1000, v141
	v_ashrrev_i32_e32 v147, 31, v146
	s_add_i32 s6, s6, 16
	s_cmpk_eq_i32 s6, 0x400
	s_waitcnt vmcnt(1)
	v_cndmask_b32_e64 v55, v151, 0, s[4:5]
	v_cndmask_b32_e64 v54, v150, 0, s[4:5]
	v_cndmask_b32_e64 v53, v149, 0, s[4:5]
	v_cndmask_b32_e64 v52, v148, 0, s[4:5]
	ds_write_b128 v109, v[148:151] offset:16896
	global_load_dwordx4 v[148:151], v[96:97], off
	v_lshl_add_u64 v[96:97], v[96:97], 0, s[56:57]
	s_nop 0
	v_mfma_f32_16x16x32_bf16 v[56:59], v[52:55], v[0:3], 0
	v_mfma_f32_16x16x32_bf16 v[60:63], v[52:55], v[4:7], 0
	v_mfma_f32_16x16x32_bf16 v[64:67], v[52:55], v[8:11], 0
	v_mfma_f32_16x16x32_bf16 v[68:71], v[52:55], v[16:19], 0
	v_mfma_f32_16x16x32_bf16 v[72:75], v[52:55], v[12:15], 0
	v_mfma_f32_16x16x32_bf16 v[76:79], v[52:55], v[20:23], 0
	v_mfma_f32_16x16x32_bf16 v[142:145], v[52:55], v[24:27], 0
	v_mfma_f32_16x16x32_bf16 v[48:51], v[52:55], v[28:31], 0
	s_nop 1
	ds_write2_b32 v124, v56, v60 offset1:16
	ds_write2_b32 v124, v57, v61 offset0:132 offset1:148
	ds_write2_b32 v125, v58, v62 offset0:8 offset1:24
	ds_write2_b32 v125, v59, v63 offset0:140 offset1:156
	ds_write2_b32 v124, v64, v68 offset0:32 offset1:48
	ds_write2_b32 v124, v65, v69 offset0:164 offset1:180
	ds_write2_b32 v125, v66, v70 offset0:40 offset1:56
	ds_write2_b32 v125, v67, v71 offset0:172 offset1:188
	ds_write2_b32 v124, v72, v76 offset0:64 offset1:80
	ds_write2_b32 v124, v73, v77 offset0:196 offset1:212
	ds_write2_b32 v125, v74, v78 offset0:72 offset1:88
	ds_write2_b32 v125, v75, v79 offset0:204 offset1:220
	ds_write2_b32 v124, v142, v48 offset0:96 offset1:112
	ds_write2_b32 v124, v143, v49 offset0:228 offset1:244
	ds_write2_b32 v125, v144, v50 offset0:104 offset1:120
	ds_write2_b32 v125, v145, v51 offset0:236 offset1:252
	s_waitcnt lgkmcnt(0)
	ds_read2st64_b32 v[222:223], v111 offset0:16 offset1:17
	ds_read2st64_b32 v[224:225], v126 offset0:18 offset1:19
	ds_read2st64_b32 v[226:227], v127 offset0:20 offset1:21
	ds_read2st64_b32 v[228:229], v128 offset0:22 offset1:23
	s_waitcnt lgkmcnt(3)
	v_fma_f32 v160, v94, v158, v222
	v_fma_f32 v161, v94, v159, v223
	v_fma_f32 v162, -v95, v159, v160
	v_fma_f32 v163, v95, v158, v161
	ds_read2st64_b32 v[230:231], v129 offset0:24 offset1:25
	v_cvt_pk_bf16_f32 v164, v162, v83
	v_cvt_pk_bf16_f32 v165, v163, v83
	ds_write_b16 v118, v164 offset:12544
	ds_write_b16 v118, v165 offset:12672
	s_waitcnt lgkmcnt(5)
	v_fma_f32 v160, v94, v162, v224
	v_fma_f32 v161, v94, v163, v225
	v_fma_f32 v158, -v95, v163, v160
	v_fma_f32 v159, v95, v162, v161
	ds_read2st64_b32 v[232:233], v130 offset0:26 offset1:27
	v_cvt_pk_bf16_f32 v166, v158, v83
	v_cvt_pk_bf16_f32 v167, v159, v83
	ds_write_b16 v118, v166 offset:12816
	ds_write_b16 v118, v167 offset:12944
	s_waitcnt lgkmcnt(7)
	v_fma_f32 v160, v94, v158, v226
	v_fma_f32 v161, v94, v159, v227
	v_fma_f32 v162, -v95, v159, v160
	v_fma_f32 v163, v95, v158, v161
	ds_read2st64_b32 v[234:235], v131 offset0:28 offset1:29
	v_cvt_pk_bf16_f32 v164, v162, v83
	v_cvt_pk_bf16_f32 v165, v163, v83
	ds_write_b16 v118, v164 offset:13088
	ds_write_b16 v118, v165 offset:13216
	s_waitcnt lgkmcnt(9)
	v_fma_f32 v160, v94, v162, v228
	v_fma_f32 v161, v94, v163, v229
	v_fma_f32 v158, -v95, v163, v160
	v_fma_f32 v159, v95, v162, v161
	ds_read2st64_b32 v[236:237], v132 offset0:30 offset1:31
	v_cvt_pk_bf16_f32 v166, v158, v83
	v_cvt_pk_bf16_f32 v167, v159, v83
	ds_write_b16 v118, v166 offset:13360
	ds_write_b16 v118, v167 offset:13488
	s_waitcnt lgkmcnt(11)
	v_fma_f32 v160, v94, v158, v230
	v_fma_f32 v161, v94, v159, v231
	v_fma_f32 v162, -v95, v159, v160
	v_fma_f32 v163, v95, v158, v161
	ds_read2st64_b32 v[238:239], v133 offset0:32 offset1:33
	v_cvt_pk_bf16_f32 v164, v162, v83
	v_cvt_pk_bf16_f32 v165, v163, v83
	ds_write_b16 v118, v164 offset:13632
	ds_write_b16 v118, v165 offset:13760
	s_waitcnt lgkmcnt(11)
	v_fma_f32 v160, v94, v162, v232
	v_fma_f32 v161, v94, v163, v233
	v_fma_f32 v158, -v95, v163, v160
	v_fma_f32 v159, v95, v162, v161
	ds_read2st64_b32 v[240:241], v134 offset0:34 offset1:35
	v_cvt_pk_bf16_f32 v166, v158, v83
	v_cvt_pk_bf16_f32 v167, v159, v83
	ds_write_b16 v118, v166 offset:13904
	ds_write_b16 v118, v167 offset:14032
	s_waitcnt lgkmcnt(11)
	v_fma_f32 v160, v94, v158, v234
	v_fma_f32 v161, v94, v159, v235
	v_fma_f32 v162, -v95, v159, v160
	v_fma_f32 v163, v95, v158, v161
	ds_read2st64_b32 v[242:243], v135 offset0:36 offset1:37
	v_cvt_pk_bf16_f32 v164, v162, v83
	v_cvt_pk_bf16_f32 v165, v163, v83
	ds_write_b16 v118, v164 offset:14176
	ds_write_b16 v118, v165 offset:14304
	s_waitcnt lgkmcnt(11)
	v_fma_f32 v160, v94, v162, v236
	v_fma_f32 v161, v94, v163, v237
	v_fma_f32 v158, -v95, v163, v160
	v_fma_f32 v159, v95, v162, v161
	ds_read2st64_b32 v[244:245], v136 offset0:38 offset1:39
	v_cvt_pk_bf16_f32 v166, v158, v83
	v_cvt_pk_bf16_f32 v167, v159, v83
	ds_write_b16 v118, v166 offset:14448
	ds_write_b16 v118, v167 offset:14576
	s_waitcnt lgkmcnt(11)
; #define LAS __attribute__((address_space(3)))
; __device__ __forceinline__ unsigned pk2(float lo, float hi) { unsigned r; asm volatile("v_cvt_pk_bf16_f32 %0, %1, %2" : "=v"(r) : "v"(lo), "v"(hi)); return r; }
; __device__ __forceinline__ float gelu_tanh(float x) { return x * sigm(1.5957691216f * (x + 0.044715f * x * x * x)); }
; #define LDS_WAIT() asm volatile("s_waitcnt lgkmcnt(0)" ::: "memory")
; #define MFMA16(a, b, c) __builtin_amdgcn_mfma_f32_16x16x32_bf16(a, b, c, 0, 0, 0)
; __device__ __forceinline__ bf16_t tobf(float x) { return (bf16_t)pk2(x, 0.f); }
; __device__ __forceinline__ void s5_phase(LAS unsigned char* lds, const bf16_t* USSM, const float* S5A, const float* S5B, const float* c_re, const float* c_im, const float* dskip,
;                                          bf16_t* YSSM, int tid, int lane, int wave) {
;     ...
;             for (int t = 0; t < 16; ++t) { const float br = BU[t * 132 + lane], bi = BU[t * 132 + 64 + lane];
;                 const float nr = are * xr - aim * xi + br, ni = are * xi + aim * xr + bi; xr = nr; xi = ni;
;                 XB[t * 136 + lane] = tobf(xr); XB[t * 136 + 64 + lane] = tobf(xi); }
;             LDS_WAIT();
;             f32x4 y = z4;
; #pragma unroll
;             for (int ks = 0; ks < 4; ++ks) y = MFMA16(*(const LAS bf16x8*)(XB + r16 * 136 + ks * 32 + q4 * 8), cfr[ks], y);
; #pragma unroll
;             for (int i = 0; i < 4; ++i) { const float u = bflo((unsigned)UST[(q4 * 4 + i) * 16 + r16]); BU[(q4 * 4 + i) * 16 + r16] = gelu_tanh(y[i] + dsk * u); }
;             LDS_WAIT();
;             { const f32x4 v = *(const LAS f32x4*)(BU + (lane >> 2) * 16 + (lane & 3) * 4); u32x2 o; o.x = pk2(v[0], v[1]); o.y = pk2(v[2], v[3]);
;               *(u32x2*)(YSSM + ((size_t)(b * SEQ + wave * 1024 + tb * 16 + (lane >> 2))) * 1024 + g * 16 + (lane & 3) * 4) = o; }
;             LDS_WAIT();
;         }
	v_fma_f32 v160, v94, v158, v238
	v_fma_f32 v161, v94, v159, v239
	v_fma_f32 v162, -v95, v159, v160
	v_fma_f32 v163, v95, v158, v161
	ds_read2st64_b32 v[246:247], v137 offset0:40 offset1:41
	v_cvt_pk_bf16_f32 v164, v162, v83
	v_cvt_pk_bf16_f32 v165, v163, v83
	ds_write_b16 v118, v164 offset:14720
	ds_write_b16 v118, v165 offset:14848
	s_waitcnt lgkmcnt(11)
	v_fma_f32 v160, v94, v162, v240
	v_fma_f32 v161, v94, v163, v241
	v_fma_f32 v158, -v95, v163, v160
	v_fma_f32 v159, v95, v162, v161
	ds_read2st64_b32 v[248:249], v138 offset0:42 offset1:43
	v_cvt_pk_bf16_f32 v166, v158, v83
	v_cvt_pk_bf16_f32 v167, v159, v83
	ds_write_b16 v118, v166 offset:14992
	ds_write_b16 v118, v167 offset:15120
	s_waitcnt lgkmcnt(11)
	v_fma_f32 v160, v94, v158, v242
	v_fma_f32 v161, v94, v159, v243
	v_fma_f32 v162, -v95, v159, v160
	v_fma_f32 v163, v95, v158, v161
	ds_read2st64_b32 v[250:251], v139 offset0:44 offset1:45
	v_cvt_pk_bf16_f32 v164, v162, v83
	v_cvt_pk_bf16_f32 v165, v163, v83
	ds_write_b16 v118, v164 offset:15264
	ds_write_b16 v118, v165 offset:15392
	s_waitcnt lgkmcnt(11)
	v_fma_f32 v160, v94, v162, v244
	v_fma_f32 v161, v94, v163, v245
	v_fma_f32 v158, -v95, v163, v160
	v_fma_f32 v159, v95, v162, v161
	ds_read2st64_b32 v[252:253], v140 offset0:46 offset1:47
	v_cvt_pk_bf16_f32 v166, v158, v83
	v_cvt_pk_bf16_f32 v167, v159, v83
	ds_write_b16 v118, v166 offset:15536
	ds_write_b16 v118, v167 offset:15664
	s_waitcnt lgkmcnt(11)
	v_fma_f32 v160, v94, v158, v246
	v_fma_f32 v161, v94, v159, v247
	v_fma_f32 v162, -v95, v159, v160
	v_fma_f32 v163, v95, v158, v161
	v_cvt_pk_bf16_f32 v164, v162, v83
	v_cvt_pk_bf16_f32 v165, v163, v83
	ds_write_b16 v118, v164 offset:15808
	ds_write_b16 v118, v165 offset:15936
	s_waitcnt lgkmcnt(10)
	v_fma_f32 v160, v94, v162, v248
	v_fma_f32 v161, v94, v163, v249
	v_fma_f32 v158, -v95, v163, v160
	v_fma_f32 v159, v95, v162, v161
	v_cvt_pk_bf16_f32 v166, v158, v83
	v_cvt_pk_bf16_f32 v167, v159, v83
	ds_write_b16 v118, v166 offset:16080
	ds_write_b16 v118, v167 offset:16208
	s_waitcnt lgkmcnt(9)
	v_fma_f32 v160, v94, v158, v250
	v_fma_f32 v161, v94, v159, v251
	v_fma_f32 v162, -v95, v159, v160
	v_fma_f32 v163, v95, v158, v161
	v_cvt_pk_bf16_f32 v164, v162, v83
	v_cvt_pk_bf16_f32 v165, v163, v83
	ds_write_b16 v118, v164 offset:16352
	ds_write_b16 v118, v165 offset:16480
	s_waitcnt lgkmcnt(8)
	v_fma_f32 v160, v94, v162, v252
	v_fma_f32 v161, v94, v163, v253
	v_fma_f32 v76, -v95, v163, v160
	v_fma_f32 v77, v95, v162, v161
	v_cvt_pk_bf16_f32 v166, v76, v83
	v_cvt_pk_bf16_f32 v167, v77, v83
	ds_write_b16 v118, v166 offset:16624
	ds_write_b16 v118, v167 offset:16752
	s_waitcnt lgkmcnt(0)
	ds_read_b128 v[48:51], v119 offset:12544
	ds_read_b128 v[52:55], v119 offset:12608
	ds_read_b128 v[56:59], v119 offset:12672
	s_waitcnt lgkmcnt(2)
	v_mfma_f32_16x16x32_bf16 v[48:51], v[48:51], v[32:35], 0
	ds_read_b128 v[60:63], v119 offset:12736
	ds_read_u16 v64, v113 offset:16896
	ds_read_u16 v65, v115 offset:16928
	s_waitcnt lgkmcnt(4)
	v_mfma_f32_16x16x32_bf16 v[48:51], v[52:55], v[36:39], v[48:51]
	ds_read_u16 v52, v115 offset:16960
	ds_read_u16 v53, v115 offset:16992
	s_waitcnt lgkmcnt(3)
	v_lshlrev_b32_e32 v54, 16, v64
	s_waitcnt lgkmcnt(2)
	v_lshlrev_b32_e32 v55, 16, v65
	v_mfma_f32_16x16x32_bf16 v[48:51], v[56:59], v[40:43], v[48:51]
	s_waitcnt lgkmcnt(1)
	v_lshlrev_b32_e32 v52, 16, v52
	s_waitcnt lgkmcnt(0)
	v_lshlrev_b32_e32 v53, 16, v53
	v_mfma_f32_16x16x32_bf16 v[48:51], v[60:63], v[44:47], v[48:51]
	s_nop 7
	v_fma_f32 v48, v123, v54, v48
	v_fma_f32 v49, v123, v55, v49
	v_fma_f32 v50, v123, v52, v50
	v_fmac_f32_e32 v51, v123, v53
	v_mul_f32_e32 v52, 0x3d372713, v48
	v_mul_f32_e32 v53, 0x3d372713, v49
	v_mul_f32_e32 v54, 0x3d372713, v50
	v_mul_f32_e32 v55, 0x3d372713, v51
	v_mul_f32_e32 v52, v48, v52
	v_mul_f32_e32 v53, v49, v53
	v_mul_f32_e32 v54, v50, v54
	v_mul_f32_e32 v55, v51, v55
	v_fma_f32 v52, v48, v52, v48
	v_fma_f32 v53, v49, v53, v49
	v_fma_f32 v54, v50, v54, v50
	v_fma_f32 v55, v51, v55, v51
	v_mul_f32_e32 v52, 0x3fcc422a, v52
	v_mul_f32_e32 v53, 0x3fcc422a, v53
	v_mul_f32_e32 v54, 0x3fcc422a, v54
	v_mul_f32_e32 v55, 0x3fcc422a, v55
	v_mul_f32_e32 v52, 0xbfb8aa3b, v52
	v_mul_f32_e32 v53, 0xbfb8aa3b, v53
	v_mul_f32_e32 v54, 0xbfb8aa3b, v54
	v_mul_f32_e32 v55, 0xbfb8aa3b, v55
	v_exp_f32_e32 v52, v52
	v_exp_f32_e32 v53, v53
	v_exp_f32_e32 v54, v54
	v_exp_f32_e32 v55, v55
	v_add_f32_e32 v52, 1.0, v52
	v_add_f32_e32 v53, 1.0, v53
	v_add_f32_e32 v54, 1.0, v54
	v_add_f32_e32 v55, 1.0, v55
	v_rcp_f32_e32 v52, v52
	v_rcp_f32_e32 v53, v53
	v_rcp_f32_e32 v54, v54
	v_rcp_f32_e32 v55, v55
	v_mul_f32_e32 v48, v48, v52
	v_mul_f32_e32 v49, v49, v53
	v_mul_f32_e32 v50, v50, v54
	v_mul_f32_e32 v51, v51, v55
	ds_write_b32 v114, v48 offset:4096
	ds_write2_b32 v104, v49, v50 offset0:16 offset1:32
	ds_write_b32 v141, v51 offset:4288
	s_waitcnt lgkmcnt(0)
	v_lshlrev_b64 v[52:53], 11, v[146:147]
	ds_read_b128 v[48:51], v110 offset:4096
	v_lshl_add_u64 v[52:53], v[100:101], 0, v[52:53]
	s_waitcnt lgkmcnt(0)
	v_cvt_pk_bf16_f32 v48, v48, v49
	v_cvt_pk_bf16_f32 v49, v50, v51
	global_store_dwordx2 v[52:53], v[48:49], off
	s_waitcnt lgkmcnt(0)
	s_cbranch_scc0 .LBB0_596
	s_add_i32 s43, s43, s84
	s_add_i32 s27, s27, s33
	s_add_i32 s42, s42, s84
	s_cmpk_gt_i32 s43, 0xff
	s_cbranch_scc0 .LBB0_568
